# mla_finalize: latent wave_sum, per-head 4-lane sums and rope partner exchanges via DPP (row_shr/bcast scan, quad_perm) instead of ds_bpermute; on top of v19
# speedup vs baseline: 1.0082x; 1.0008x over previous
; DI float bflo(unsigned w) { return __uint_as_float(w << 16); }
; DI float bfhi(unsigned w) { return __uint_as_float(w & 0xffff0000u); }
; DI void mla_finalize(PPtr p, int j, ldsp lds, int tid, int wave, int lane) {
;     ...
;             const float rq = rsqrtf(wave_sum(ssq) * (1.0f / QL) + EPS), rkv = rsqrtf(wave_sum(sskv) * (1.0f / KVL) + EPS);
;             float cs, sn;
;             { const int fi = lane & 15; const float inv = exp2f(-(float)fi * (13.287712379549449f / 16.0f));
;               const float ang = (float)p->pos[t] * inv; double rev = (double)ang * 0.15915494309189535; rev -= floor(rev); const float rv = (float)rev;
;               cs = __builtin_amdgcn_cosf(rv); sn = __builtin_amdgcn_sinf(rv); }
;             float cj[8], sj[8];
; #pragma unroll
;             for (int i = 0; i < 8; ++i) { cj[i] = __shfl(cs, 8 * (sub & 1) + i); sj[i] = __shfl(sn, 8 * (sub & 1) + i); }
; #pragma unroll
;             for (int which = 0; which < 2; ++which) {
;                 float v[24];
;                 if (which == 0) {
;                     const bf16_t* src = qraw + (size_t)t * 1536 + head * QKH;
; #pragma unroll
;                     for (int g = 0; g < 3; ++g) { const u32x4 w = *(const u32x4*)(src + 8 * (sub + 4 * g));
; #pragma unroll
;                         for (int i = 0; i < 4; ++i) { v[8 * g + 2 * i] = bflo(w[i]) * rq; v[8 * g + 2 * i + 1] = bfhi(w[i]) * rq; } }
.LBB0_786:
	s_or_b64 exec, exec, s[10:11]
	s_lshl_b64 s[10:11], s[14:15], 2
	s_add_u32 s10, s12, s10
	s_addc_u32 s11, s13, s11
	s_mov_b32 s10, 0x6dc9c883
	s_mov_b32 s11, 0x3fc45f30
	v_lshl_add_u64 v[106:107], v[64:65], 0, s[8:9]
	s_mov_b32 s8, 0x3b2aaaab
	s_mov_b32 s9, 0x3b800000
	v_mov_b32_e32 v69, v1
	s_nop 1
	v_add_f32_dpp v2, v2, v2 row_shr:1 row_mask:0xf bank_mask:0xf bound_ctrl:0
	v_add_f32_dpp v3, v3, v3 row_shr:1 row_mask:0xf bank_mask:0xf bound_ctrl:0
	s_nop 0
	v_add_f32_dpp v2, v2, v2 row_shr:2 row_mask:0xf bank_mask:0xf bound_ctrl:0
	v_add_f32_dpp v3, v3, v3 row_shr:2 row_mask:0xf bank_mask:0xf bound_ctrl:0
	s_nop 0
	v_add_f32_dpp v2, v2, v2 row_shr:4 row_mask:0xf bank_mask:0xf bound_ctrl:0
	v_add_f32_dpp v3, v3, v3 row_shr:4 row_mask:0xf bank_mask:0xf bound_ctrl:0
	s_nop 0
	v_add_f32_dpp v2, v2, v2 row_shr:8 row_mask:0xf bank_mask:0xf bound_ctrl:0
	v_add_f32_dpp v3, v3, v3 row_shr:8 row_mask:0xf bank_mask:0xf bound_ctrl:0
	s_nop 0
	v_add_f32_dpp v2, v2, v2 row_bcast:15 row_mask:0xa bank_mask:0xf
	v_add_f32_dpp v3, v3, v3 row_bcast:15 row_mask:0xa bank_mask:0xf
	s_nop 0
	v_add_f32_dpp v2, v2, v2 row_bcast:31 row_mask:0xc bank_mask:0xf
	v_add_f32_dpp v3, v3, v3 row_bcast:31 row_mask:0xc bank_mask:0xf
	s_nop 0
	v_readlane_b32 s30, v2, 63
	v_readlane_b32 s31, v3, 63
	s_nop 1
	v_mov_b32_e32 v2, s30
	v_mov_b32_e32 v3, s31
	s_nop 0
	v_pk_fma_f32 v[2:3], v[2:3], s[8:9], v[152:153] op_sel_hi:[1,1,0]
	v_mov_b32_e32 v6, v179
	v_cvt_f32_i32_e32 v6, v6
	v_mul_f32_e32 v4, 0x4b800000, v3
	v_cmp_gt_f32_e64 s[8:9], s91, v2
	v_mul_f32_e32 v6, v134, v6
	v_cvt_f64_f32_e32 v[6:7], v6
	v_mul_f64 v[8:9], v[6:7], s[10:11]
	v_floor_f64_e32 v[8:9], v[8:9]
	v_fma_f64 v[6:7], v[6:7], s[10:11], -v[8:9]
	v_cvt_f32_f64_e32 v6, v[6:7]
	v_cos_f32_e32 v7, v6
	v_sin_f32_e32 v6, v6
	s_lshl_b64 s[10:11], s[14:15], 4
	v_or_b32_e32 v8, s10, v38
	ds_bpermute_b32 v100, v135, v7
	ds_bpermute_b32 v102, v135, v6
	ds_bpermute_b32 v101, v136, v7
	ds_bpermute_b32 v105, v136, v6
	ds_bpermute_b32 v94, v137, v7
	ds_bpermute_b32 v96, v137, v6
	ds_bpermute_b32 v95, v138, v7
	ds_bpermute_b32 v99, v138, v6
	ds_bpermute_b32 v88, v139, v7
	ds_bpermute_b32 v90, v139, v6
	ds_bpermute_b32 v89, v140, v7
	ds_bpermute_b32 v93, v140, v6
	ds_bpermute_b32 v80, v141, v7
	ds_bpermute_b32 v82, v141, v6
	ds_bpermute_b32 v81, v142, v7
	ds_bpermute_b32 v87, v142, v6
	v_mov_b64_e32 v[6:7], s[2:3]
	s_movk_i32 s10, 0xc0
	v_mad_u64_u32 v[84:85], s[22:23], v8, s10, v[6:7]
	v_mov_b32_e32 v6, 0xc0
	v_mad_i32_i24 v85, s11, v6, v85
	s_lshl_b64 s[10:11], s[14:15], 12
	v_lshl_add_u64 v[78:79], v[40:41], 0, s[10:11]
	v_cmp_gt_f32_e64 s[10:11], s91, v3
	s_nop 1
	v_cndmask_b32_e64 v3, v3, v4, s[10:11]
	v_rsq_f32_e32 v3, v3
	s_nop 0
	v_mul_f32_e32 v4, 0x45800000, v3
	v_cndmask_b32_e64 v76, v3, v4, s[10:11]
	v_mul_f32_e32 v3, 0x4b800000, v2
	v_cndmask_b32_e64 v2, v2, v3, s[8:9]
	v_rsq_f32_e32 v2, v2
	s_nop 0
	v_mul_f32_e32 v3, 0x45800000, v2
	v_cndmask_b32_e64 v86, v2, v3, s[8:9]
	v_mov_b32_e32 v2, 0xc00
	v_mad_i64_i32 v[2:3], s[8:9], s14, v2, v[66:67]
	s_mov_b64 s[8:9], 0x15a40000
	v_lshl_add_u64 v[110:111], v[84:85], 0, s[8:9]
	v_lshl_add_u64 v[168:169], v[110:111], 0, v[68:69]
	s_add_i32 s14, s14, 1
	v_mov_b32_e32 v34, v192
	v_mov_b32_e32 v35, v193
	v_mov_b32_e32 v36, v194
	v_mov_b32_e32 v37, v195
	v_lshlrev_b32_e32 v118, 16, v36
	v_and_b32_e32 v119, 0xffff0000, v36
	v_mov_b32_e32 v10, v196
	v_mov_b32_e32 v11, v197
	v_mov_b32_e32 v12, v198
	v_mov_b32_e32 v13, v199
	v_mov_b32_e32 v6, v206
	v_mov_b32_e32 v7, v207
	v_mov_b32_e32 v8, v208
	v_mov_b32_e32 v9, v209
	v_and_b32_e32 v2, 0xffff0000, v8
	v_lshlrev_b32_e32 v3, 16, v8
	s_waitcnt lgkmcnt(0)
	v_pk_mul_f32 v[108:109], v[86:87], v[2:3] op_sel_hi:[0,1]
	v_and_b32_e32 v2, 0xffff0000, v9
	v_lshlrev_b32_e32 v3, 16, v9
	v_pk_mul_f32 v[8:9], v[86:87], v[2:3] op_sel_hi:[0,1]
	global_load_dwordx4 v[22:25], v[44:45], off
	global_load_dwordx4 v[26:29], v[44:45], off offset:16
	global_load_dwordx4 v[18:21], v[44:45], off offset:128
	global_load_dwordx4 v[14:17], v[44:45], off offset:144
	global_load_dwordx4 v[2:5], v[44:45], off offset:272
	global_load_dwordx4 v[30:33], v[44:45], off offset:256
	v_lshlrev_b32_e32 v120, 16, v34
	v_and_b32_e32 v121, 0xffff0000, v34
	v_lshlrev_b32_e32 v116, 16, v37
	v_and_b32_e32 v117, 0xffff0000, v37
	v_pk_mul_f32 v[36:37], v[86:87], v[118:119] op_sel_hi:[0,1]
	v_lshlrev_b32_e32 v118, 16, v35
	v_and_b32_e32 v119, 0xffff0000, v35
	v_pk_mul_f32 v[120:121], v[86:87], v[120:121] op_sel_hi:[0,1]
	v_pk_mul_f32 v[118:119], v[86:87], v[118:119] op_sel_hi:[0,1]
	v_pk_mul_f32 v[156:157], v[120:121], v[120:121]
	v_pk_mul_f32 v[128:129], v[118:119], v[118:119]
	v_add_f32_e32 v71, v156, v157
	v_add_f32_e32 v71, v128, v71
	v_pk_mul_f32 v[126:127], v[36:37], v[36:37]
	v_add_f32_e32 v71, v129, v71
	v_pk_mul_f32 v[116:117], v[86:87], v[116:117] op_sel_hi:[0,1]
	v_add_f32_e32 v71, v126, v71
	v_pk_mul_f32 v[124:125], v[116:117], v[116:117]
	v_lshlrev_b32_e32 v166, 16, v10
	v_and_b32_e32 v167, 0xffff0000, v10
	v_add_f32_e32 v71, v127, v71
	v_lshlrev_b32_e32 v162, 16, v11
	v_and_b32_e32 v163, 0xffff0000, v11
	v_pk_mul_f32 v[10:11], v[86:87], v[166:167] op_sel_hi:[0,1]
	v_add_f32_e32 v71, v124, v71
	v_pk_mul_f32 v[166:167], v[10:11], v[10:11]
	v_add_f32_e32 v71, v125, v71
	v_pk_mul_f32 v[162:163], v[86:87], v[162:163] op_sel_hi:[0,1]
	v_add_f32_e32 v71, v166, v71
	v_lshlrev_b32_e32 v160, 16, v12
	v_and_b32_e32 v161, 0xffff0000, v12
	v_pk_mul_f32 v[164:165], v[162:163], v[162:163]
	v_add_f32_e32 v71, v167, v71
	v_lshlrev_b32_e32 v122, 16, v13
	v_and_b32_e32 v123, 0xffff0000, v13
	v_pk_mul_f32 v[12:13], v[86:87], v[160:161] op_sel_hi:[0,1]
	v_add_f32_e32 v71, v164, v71
; DI unsigned pk2(float lo, float hi) { f32x2 v = {lo, hi}; bf16x2_t b = __builtin_convertvector(v, bf16x2_t); return __builtin_bit_cast(unsigned, b); }
; DI void mla_finalize(PPtr p, int j, ldsp lds, int tid, int wave, int lane) {
;     ...
;                 float ss = 0.f;
; #pragma unroll
;                 for (int i = 0; i < 24; ++i) ss += v[i] * v[i];
;                 ss += __shfl_xor(ss, 1); ss += __shfl_xor(ss, 2);
;                 const float rs = rsqrtf(ss * (1.0f / QKH) + EPS);
;                 const float* gn = which == 0 ? qg : kg;
; #pragma unroll
;                 for (int g = 0; g < 3; ++g) { const f32x4 g0 = *(const f32x4*)(gn + 8 * (sub + 4 * g)), g1 = *(const f32x4*)(gn + 8 * (sub + 4 * g) + 4);
; #pragma unroll
;                     for (int i = 0; i < 4; ++i) { v[8 * g + i] *= rs * g0[i]; v[8 * g + 4 + i] *= rs * g1[i]; } }
; #pragma unroll
;                 for (int i = 0; i < 8; ++i) { const float mine = v[16 + i], other = __shfl_xor(mine, 2);
;                     v[16 + i] = (sub < 2) ? (mine * cj[i] - other * sj[i]) : (other * sj[i] + mine * cj[i]); }
;                 const float osc = which == 0 ? QSCALE : 1.0f;
;                 bf16_t* dst = (which == 0 ? Qb : Kb) + ((size_t)t * HEADS + head) * QKH;
; #pragma unroll
;                 for (int g = 0; g < 3; ++g) { u32x4 w;
; #pragma unroll
;                     for (int i = 0; i < 4; ++i) w[i] = pk2(v[8 * g + 2 * i] * osc, v[8 * g + 2 * i + 1] * osc);
;                     *(u32x4*)(dst + 8 * (sub + 4 * g)) = w; }
	v_pk_mul_f32 v[160:161], v[12:13], v[12:13]
	v_add_f32_e32 v71, v165, v71
	v_pk_mul_f32 v[122:123], v[86:87], v[122:123] op_sel_hi:[0,1]
	v_add_f32_e32 v71, v160, v71
	v_pk_mul_f32 v[158:159], v[122:123], v[122:123]
	v_lshlrev_b32_e32 v174, 16, v6
	v_and_b32_e32 v175, 0xffff0000, v6
	v_add_f32_e32 v71, v161, v71
	v_lshlrev_b32_e32 v170, 16, v7
	v_and_b32_e32 v171, 0xffff0000, v7
	v_pk_mul_f32 v[6:7], v[86:87], v[174:175] op_sel_hi:[0,1]
	v_add_f32_e32 v71, v158, v71
	v_pk_mul_f32 v[174:175], v[6:7], v[6:7]
	v_add_f32_e32 v71, v159, v71
	v_pk_mul_f32 v[170:171], v[86:87], v[170:171] op_sel_hi:[0,1]
	v_add_f32_e32 v71, v174, v71
	v_pk_mul_f32 v[172:173], v[170:171], v[170:171]
	v_add_f32_e32 v71, v175, v71
	v_add_f32_e32 v71, v172, v71
	v_pk_mul_f32 v[112:113], v[108:109], v[108:109]
	v_add_f32_e32 v71, v173, v71
	v_add_f32_e32 v71, v113, v71
	v_pk_mul_f32 v[114:115], v[8:9], v[8:9]
	v_add_f32_e32 v71, v112, v71
	v_add_f32_e32 v71, v115, v71
	v_add_f32_e32 v71, v114, v71
	s_nop 1
	v_add_f32_dpp v71, v71, v71 quad_perm:[1,0,3,2] row_mask:0xf bank_mask:0xf
	v_lshl_add_u64 v[34:35], v[110:111], 0, v[0:1]
	s_nop 0
	v_add_f32_dpp v71, v71, v71 quad_perm:[2,3,0,1] row_mask:0xf bank_mask:0xf
	v_fmamk_f32 v71, v71, 0x3c2aaaab, v152
	v_cmp_gt_f32_e64 s[8:9], s91, v71
	v_mul_f32_e32 v73, 0x4b800000, v71
	s_nop 0
	v_cndmask_b32_e64 v71, v71, v73, s[8:9]
	v_rsq_f32_e32 v71, v71
	s_nop 0
	v_mul_f32_e32 v73, 0x45800000, v71
	v_cndmask_b32_e64 v86, v71, v73, s[8:9]
	s_waitcnt vmcnt(3)
	v_pk_mul_f32 v[18:19], v[18:19], v[86:87] op_sel_hi:[1,0]
	v_pk_mul_f32 v[22:23], v[22:23], v[86:87] op_sel_hi:[1,0]
	v_pk_mul_f32 v[18:19], v[10:11], v[18:19]
	s_waitcnt vmcnt(2)
	v_pk_mul_f32 v[10:11], v[14:15], v[86:87] op_sel_hi:[1,0]
	v_pk_mul_f32 v[24:25], v[24:25], v[86:87] op_sel_hi:[1,0]
	v_pk_mul_f32 v[14:15], v[12:13], v[10:11]
	v_pk_mul_f32 v[10:11], v[20:21], v[86:87] op_sel_hi:[1,0]
	v_pk_mul_f32 v[22:23], v[120:121], v[22:23]
	v_pk_mul_f32 v[20:21], v[162:163], v[10:11]
	v_pk_mul_f32 v[10:11], v[16:17], v[86:87] op_sel_hi:[1,0]
	v_pk_mul_f32 v[26:27], v[26:27], v[86:87] op_sel_hi:[1,0]
	v_pk_mul_f32 v[16:17], v[122:123], v[10:11]
	s_waitcnt vmcnt(0)
	v_pk_mul_f32 v[10:11], v[30:31], v[86:87] op_sel_hi:[1,0]
	v_pk_mul_f32 v[24:25], v[118:119], v[24:25]
	v_pk_mul_f32 v[6:7], v[6:7], v[10:11]
	v_pk_mul_f32 v[10:11], v[32:33], v[86:87] op_sel_hi:[1,0]
	s_nop 1
	v_mov_b32_dpp v104, v6 quad_perm:[2,3,0,1] row_mask:0xf bank_mask:0xf
	v_mov_b32_dpp v103, v7 quad_perm:[2,3,0,1] row_mask:0xf bank_mask:0xf
	v_pk_mul_f32 v[10:11], v[170:171], v[10:11]
	s_nop 1
	v_mov_b32_dpp v98, v10 quad_perm:[2,3,0,1] row_mask:0xf bank_mask:0xf
	v_mov_b32_dpp v97, v11 quad_perm:[2,3,0,1] row_mask:0xf bank_mask:0xf
	v_pk_mul_f32 v[28:29], v[28:29], v[86:87] op_sel_hi:[1,0]
	s_waitcnt lgkmcnt(2)
	v_pk_mul_f32 v[12:13], v[104:105], v[102:103]
	v_pk_mul_f32 v[26:27], v[36:37], v[26:27]
	v_cndmask_b32_e64 v13, v13, -v13, s[6:7]
	v_cndmask_b32_e64 v12, v12, -v12, s[6:7]
	v_pk_fma_f32 v[6:7], v[6:7], v[100:101], v[12:13]
	s_waitcnt lgkmcnt(0)
	v_pk_mul_f32 v[12:13], v[98:99], v[96:97]
	v_pk_mul_f32 v[28:29], v[116:117], v[28:29]
	v_cndmask_b32_e64 v13, v13, -v13, s[6:7]
	v_cndmask_b32_e64 v12, v12, -v12, s[6:7]
	v_pk_fma_f32 v[30:31], v[10:11], v[94:95], v[12:13]
	v_pk_mul_f32 v[10:11], v[22:23], s[86:87] op_sel_hi:[1,0]
	v_pk_mul_f32 v[12:13], v[24:25], s[86:87] op_sel_hi:[1,0]
	v_pk_mul_f32 v[2:3], v[2:3], v[86:87] op_sel_hi:[1,0]
	v_cvt_pk_bf16_f32 v10, v10, v11
	v_cvt_pk_bf16_f32 v11, v12, v13
	v_pk_mul_f32 v[12:13], v[26:27], s[86:87] op_sel_hi:[1,0]
	v_pk_mul_f32 v[22:23], v[28:29], s[86:87] op_sel_hi:[1,0]
	v_pk_mul_f32 v[2:3], v[108:109], v[2:3] op_sel:[1,0] op_sel_hi:[0,1]
	v_cvt_pk_bf16_f32 v12, v12, v13
	v_cvt_pk_bf16_f32 v13, v22, v23
	s_nop 1
	v_mov_b32_dpp v92, v2 quad_perm:[2,3,0,1] row_mask:0xf bank_mask:0xf
	v_mov_b32_dpp v91, v3 quad_perm:[2,3,0,1] row_mask:0xf bank_mask:0xf
	global_store_dwordx4 v[34:35], v[10:13], off
	v_pk_mul_f32 v[6:7], v[6:7], s[86:87] op_sel_hi:[1,0]
	v_mov_b32_e32 v71, v1
	v_pk_mul_f32 v[10:11], v[18:19], s[86:87] op_sel_hi:[1,0]
	v_pk_mul_f32 v[12:13], v[20:21], s[86:87] op_sel_hi:[1,0]
	v_cvt_pk_bf16_f32 v10, v10, v11
	v_cvt_pk_bf16_f32 v11, v12, v13
	v_pk_mul_f32 v[12:13], v[14:15], s[86:87] op_sel_hi:[1,0]
	v_pk_mul_f32 v[14:15], v[16:17], s[86:87] op_sel_hi:[1,0]
	v_cvt_pk_bf16_f32 v12, v12, v13
	v_cvt_pk_bf16_f32 v13, v14, v15
	global_store_dwordx4 v[168:169], v[10:13], off
	v_mov_b32_e32 v103, v105
	v_mov_b32_e32 v97, v99
	v_cvt_pk_bf16_f32 v10, v6, v7
	v_pk_mul_f32 v[6:7], v[30:31], s[86:87] op_sel_hi:[1,0]
	s_nop 0
	v_cvt_pk_bf16_f32 v11, v6, v7
	s_waitcnt lgkmcnt(0)
	v_pk_mul_f32 v[6:7], v[92:93], v[90:91]
	v_mov_b32_e32 v91, v93
	v_cndmask_b32_e64 v7, v7, -v7, s[6:7]
	v_cndmask_b32_e64 v6, v6, -v6, s[6:7]
	v_pk_fma_f32 v[2:3], v[2:3], v[88:89], v[6:7]
	s_nop 0
	v_pk_mul_f32 v[2:3], v[2:3], s[86:87] op_sel_hi:[1,0]
	s_nop 0
	v_cvt_pk_bf16_f32 v12, v2, v3
	v_pk_mul_f32 v[2:3], v[4:5], v[86:87] op_sel_hi:[1,0]
	s_nop 0
	v_pk_mul_f32 v[2:3], v[8:9], v[2:3] op_sel:[1,0] op_sel_hi:[0,1]
	s_nop 1
	v_mov_b32_dpp v86, v2 quad_perm:[2,3,0,1] row_mask:0xf bank_mask:0xf
	v_mov_b32_dpp v83, v3 quad_perm:[2,3,0,1] row_mask:0xf bank_mask:0xf
	s_waitcnt lgkmcnt(0)
; DI unsigned pk2(float lo, float hi) { f32x2 v = {lo, hi}; bf16x2_t b = __builtin_convertvector(v, bf16x2_t); return __builtin_bit_cast(unsigned, b); }
; DI float bflo(unsigned w) { return __uint_as_float(w << 16); }
; DI float bfhi(unsigned w) { return __uint_as_float(w & 0xffff0000u); }
; DI void mla_finalize(PPtr p, int j, ldsp lds, int tid, int wave, int lane) {
;     ...
;                     const bf16_t* src = kvraw + (size_t)t * 2048 + head * 128;
; #pragma unroll
;                     for (int g = 0; g < 2; ++g) { const u32x4 w = *(const u32x4*)(src + 8 * (sub + 4 * g));
; #pragma unroll
;                         for (int i = 0; i < 4; ++i) { v[8 * g + 2 * i] = bflo(w[i]) * rkv; v[8 * g + 2 * i + 1] = bfhi(w[i]) * rkv; } }
;                     const u32x4 w = *(const u32x4*)(aout + (size_t)t * ADIMP + QL + KVL + 8 * sub);
; #pragma unroll
;                     for (int i = 0; i < 4; ++i) { v[16 + 2 * i] = bflo(w[i]); v[16 + 2 * i + 1] = bfhi(w[i]); }
;                 }
;                 float ss = 0.f;
; #pragma unroll
;                 for (int i = 0; i < 24; ++i) ss += v[i] * v[i];
;                 ss += __shfl_xor(ss, 1); ss += __shfl_xor(ss, 2);
;                 const float rs = rsqrtf(ss * (1.0f / QKH) + EPS);
;                 const float* gn = which == 0 ? qg : kg;
; #pragma unroll
;                 for (int g = 0; g < 3; ++g) { const f32x4 g0 = *(const f32x4*)(gn + 8 * (sub + 4 * g)), g1 = *(const f32x4*)(gn + 8 * (sub + 4 * g) + 4);
; #pragma unroll
;                     for (int i = 0; i < 4; ++i) { v[8 * g + i] *= rs * g0[i]; v[8 * g + 4 + i] *= rs * g1[i]; } }
; #pragma unroll
;                 for (int i = 0; i < 8; ++i) { const float mine = v[16 + i], other = __shfl_xor(mine, 2);
;                     v[16 + i] = (sub < 2) ? (mine * cj[i] - other * sj[i]) : (other * sj[i] + mine * cj[i]); }
;                 const float osc = which == 0 ? QSCALE : 1.0f;
;                 bf16_t* dst = (which == 0 ? Qb : Kb) + ((size_t)t * HEADS + head) * QKH;
; #pragma unroll
;                 for (int g = 0; g < 3; ++g) { u32x4 w;
; #pragma unroll
;                     for (int i = 0; i < 4; ++i) w[i] = pk2(v[8 * g + 2 * i] * osc, v[8 * g + 2 * i + 1] * osc);
;                     *(u32x4*)(dst + 8 * (sub + 4 * g)) = w; }
	v_pk_mul_f32 v[4:5], v[86:87], v[82:83]
	s_nop 0
	v_cndmask_b32_e64 v5, v5, -v5, s[6:7]
	v_cndmask_b32_e64 v4, v4, -v4, s[6:7]
	v_pk_fma_f32 v[2:3], v[2:3], v[80:81], v[4:5]
	v_mov_b32_e32 v83, v87
	v_pk_mul_f32 v[2:3], v[2:3], s[86:87] op_sel_hi:[1,0]
	v_mov_b32_e32 v6, v188
	v_mov_b32_e32 v7, v189
	v_mov_b32_e32 v8, v190
	v_mov_b32_e32 v9, v191
	v_lshlrev_b32_e32 v166, 16, v6
	v_cvt_pk_bf16_f32 v13, v2, v3
	v_lshl_add_u64 v[2:3], v[110:111], 0, v[70:71]
	global_store_dwordx4 v[2:3], v[10:13], off
	v_and_b32_e32 v167, 0xffff0000, v6
	v_lshlrev_b32_e32 v162, 16, v7
	v_lshl_add_u64 v[10:11], v[78:79], 0, v[0:1]
	v_and_b32_e32 v163, 0xffff0000, v7
	v_pk_mul_f32 v[6:7], v[166:167], v[166:167]
	v_pk_mul_f32 v[164:165], v[162:163], v[162:163]
	v_and_b32_e32 v10, 0xffff0000, v8
	v_lshlrev_b32_e32 v11, 16, v8
	v_pk_mul_f32 v[32:33], v[10:11], v[10:11]
	v_and_b32_e32 v8, 0xffff0000, v9
	v_lshlrev_b32_e32 v9, 16, v9
	v_pk_mul_f32 v[34:35], v[8:9], v[8:9]
	v_mov_b32_e32 v2, v210
	v_mov_b32_e32 v3, v211
	v_mov_b32_e32 v4, v212
	v_mov_b32_e32 v5, v213
	v_lshlrev_b32_e32 v24, 16, v5
	v_and_b32_e32 v25, 0xffff0000, v5
	v_pk_mul_f32 v[36:37], v[76:77], v[24:25] op_sel_hi:[0,1]
	v_lshlrev_b32_e32 v24, 16, v4
	v_and_b32_e32 v25, 0xffff0000, v4
	v_lshlrev_b32_e32 v4, 16, v3
	v_and_b32_e32 v5, 0xffff0000, v3
	v_pk_mul_f32 v[112:113], v[76:77], v[4:5] op_sel_hi:[0,1]
	v_lshlrev_b32_e32 v4, 16, v2
	v_and_b32_e32 v5, 0xffff0000, v2
	v_mov_b32_e32 v12, v218
	v_mov_b32_e32 v13, v219
	v_mov_b32_e32 v14, v220
	v_mov_b32_e32 v15, v221
	v_lshlrev_b32_e32 v2, 16, v15
	v_and_b32_e32 v3, 0xffff0000, v15
	v_pk_mul_f32 v[120:121], v[76:77], v[2:3] op_sel_hi:[0,1]
	v_lshlrev_b32_e32 v2, 16, v14
	v_and_b32_e32 v3, 0xffff0000, v14
	v_pk_mul_f32 v[124:125], v[76:77], v[2:3] op_sel_hi:[0,1]
	v_lshlrev_b32_e32 v2, 16, v13
	v_and_b32_e32 v3, 0xffff0000, v13
	v_pk_mul_f32 v[128:129], v[76:77], v[2:3] op_sel_hi:[0,1]
	v_lshlrev_b32_e32 v2, 16, v12
	v_and_b32_e32 v3, 0xffff0000, v12
	v_pk_mul_f32 v[108:109], v[76:77], v[24:25] op_sel_hi:[0,1]
	v_pk_mul_f32 v[116:117], v[76:77], v[4:5] op_sel_hi:[0,1]
	v_pk_mul_f32 v[158:159], v[76:77], v[2:3] op_sel_hi:[0,1]
	v_pk_mul_f32 v[118:119], v[116:117], v[116:117]
	v_pk_mul_f32 v[114:115], v[112:113], v[112:113]
	v_add_f32_e32 v73, v118, v119
	v_add_f32_e32 v73, v114, v73
	v_pk_mul_f32 v[110:111], v[108:109], v[108:109]
	v_add_f32_e32 v73, v115, v73
	v_add_f32_e32 v73, v110, v73
	v_pk_mul_f32 v[106:107], v[36:37], v[36:37]
	v_add_f32_e32 v73, v111, v73
	v_add_f32_e32 v73, v106, v73
	v_pk_mul_f32 v[160:161], v[158:159], v[158:159]
	v_add_f32_e32 v73, v107, v73
	v_add_f32_e32 v73, v160, v73
	v_pk_mul_f32 v[156:157], v[128:129], v[128:129]
	v_add_f32_e32 v73, v161, v73
	v_add_f32_e32 v73, v156, v73
	v_pk_mul_f32 v[126:127], v[124:125], v[124:125]
	v_add_f32_e32 v73, v157, v73
	v_add_f32_e32 v73, v126, v73
	v_pk_mul_f32 v[122:123], v[120:121], v[120:121]
	v_add_f32_e32 v73, v127, v73
	v_add_f32_e32 v73, v122, v73
	v_add_f32_e32 v73, v123, v73
	v_add_f32_e32 v6, v6, v73
	v_add_f32_e32 v6, v7, v6
	v_add_f32_e32 v6, v164, v6
	v_add_f32_e32 v6, v165, v6
	v_add_f32_e32 v6, v33, v6
	v_add_f32_e32 v6, v32, v6
	v_add_f32_e32 v6, v35, v6
	v_add_f32_e32 v6, v34, v6
	s_nop 1
	v_add_f32_dpp v6, v6, v6 quad_perm:[1,0,3,2] row_mask:0xf bank_mask:0xf
	v_mov_b32_e32 v73, v1
	s_nop 0
	v_add_f32_dpp v6, v6, v6 quad_perm:[2,3,0,1] row_mask:0xf bank_mask:0xf
	v_fmamk_f32 v6, v6, 0x3c2aaaab, v152
	v_cmp_gt_f32_e64 s[8:9], s91, v6
	v_mul_f32_e32 v7, 0x4b800000, v6
	s_nop 0
	v_cndmask_b32_e64 v6, v6, v7, s[8:9]
	v_rsq_f32_e32 v6, v6
	s_nop 0
	v_mul_f32_e32 v7, 0x45800000, v6
	v_cndmask_b32_e64 v6, v6, v7, s[8:9]
	v_mov_b32_e32 v16, v230
	v_mov_b32_e32 v17, v231
	v_mov_b32_e32 v18, v232
	v_mov_b32_e32 v19, v233
	v_mov_b32_e32 v20, v234
	v_mov_b32_e32 v21, v235
	v_mov_b32_e32 v22, v236
	v_mov_b32_e32 v23, v237
	v_pk_mul_f32 v[20:21], v[20:21], v[6:7] op_sel_hi:[1,0]
	v_pk_mul_f32 v[16:17], v[16:17], v[6:7] op_sel_hi:[1,0]
	v_pk_mul_f32 v[22:23], v[22:23], v[6:7] op_sel_hi:[1,0]
	v_pk_mul_f32 v[18:19], v[18:19], v[6:7] op_sel_hi:[1,0]
	s_mov_b64 s[8:9], 0x18a40000
	v_pk_mul_f32 v[20:21], v[116:117], v[20:21]
	v_pk_mul_f32 v[16:17], v[108:109], v[16:17]
	v_pk_mul_f32 v[22:23], v[112:113], v[22:23]
	v_pk_mul_f32 v[18:19], v[36:37], v[18:19]
	v_mov_b32_e32 v24, v238
	v_mov_b32_e32 v25, v239
	v_mov_b32_e32 v26, v240
	v_mov_b32_e32 v27, v241
	v_pk_mul_f32 v[24:25], v[24:25], v[6:7] op_sel_hi:[1,0]
	v_mov_b32_e32 v28, v242
	v_mov_b32_e32 v29, v243
	v_mov_b32_e32 v30, v244
	v_mov_b32_e32 v31, v245
	v_pk_mul_f32 v[28:29], v[28:29], v[6:7] op_sel_hi:[1,0]
	v_mov_b32_e32 v2, v246
	v_mov_b32_e32 v3, v247
	v_mov_b32_e32 v4, v248
	v_mov_b32_e32 v5, v249
	v_pk_mul_f32 v[2:3], v[2:3], v[6:7] op_sel_hi:[1,0]
	v_mov_b32_e32 v12, v250
	v_mov_b32_e32 v13, v251
	v_mov_b32_e32 v14, v252
	v_mov_b32_e32 v15, v253
	v_pk_mul_f32 v[12:13], v[12:13], v[6:7] op_sel_hi:[1,0]
	v_pk_mul_f32 v[2:3], v[2:3], v[10:11] op_sel:[0,1] op_sel_hi:[1,0]
	s_nop 1
	v_mov_b32_dpp v10, v2 quad_perm:[2,3,0,1] row_mask:0xf bank_mask:0xf
	v_mov_b32_dpp v11, v3 quad_perm:[2,3,0,1] row_mask:0xf bank_mask:0xf
	v_pk_mul_f32 v[12:13], v[12:13], v[166:167]
	s_nop 1
	v_mov_b32_dpp v32, v12 quad_perm:[2,3,0,1] row_mask:0xf bank_mask:0xf
	v_mov_b32_dpp v33, v13 quad_perm:[2,3,0,1] row_mask:0xf bank_mask:0xf
	v_pk_mul_f32 v[14:15], v[14:15], v[6:7] op_sel_hi:[1,0]
	s_waitcnt lgkmcnt(2)
; #define LAS __attribute__((address_space(3)))
; DI unsigned pk2(float lo, float hi) { f32x2 v = {lo, hi}; bf16x2_t b = __builtin_convertvector(v, bf16x2_t); return __builtin_bit_cast(unsigned, b); }
; DI bf16_t f2bf(float v) { return (bf16_t)(pk2(v, 0.f) & 0xffffu); }
; DI float bflo(unsigned w) { return __uint_as_float(w << 16); }
; DI float bfhi(unsigned w) { return __uint_as_float(w & 0xffff0000u); }
; DI void mla_finalize(PPtr p, int j, ldsp lds, int tid, int wave, int lane) {
;     ...
; #pragma unroll
;                 for (int i = 0; i < 8; ++i) { const float mine = v[16 + i], other = __shfl_xor(mine, 2);
;                     v[16 + i] = (sub < 2) ? (mine * cj[i] - other * sj[i]) : (other * sj[i] + mine * cj[i]); }
;                 const float osc = which == 0 ? QSCALE : 1.0f;
;                 bf16_t* dst = (which == 0 ? Qb : Kb) + ((size_t)t * HEADS + head) * QKH;
; #pragma unroll
;                 for (int g = 0; g < 3; ++g) { u32x4 w;
; #pragma unroll
;                     for (int i = 0; i < 4; ++i) w[i] = pk2(v[8 * g + 2 * i] * osc, v[8 * g + 2 * i + 1] * osc);
;                     *(u32x4*)(dst + 8 * (sub + 4 * g)) = w; }
;             }
;             { const bf16_t* src = kvraw + (size_t)t * 2048 + head * 128 + 64 + 16 * sub;
; #pragma unroll
;               for (int g = 0; g < 2; ++g) { const u32x4 w = *(const u32x4*)(src + 8 * g);
; #pragma unroll
;                   for (int i = 0; i < 4; ++i) { const int d = head * 64 + 16 * sub + 8 * g + 2 * i;
;                       *(LAS bf16_t*)(lds + ((d) * VTP + tok) * 2) = f2bf(bflo(w[i]) * rkv);
;                       *(LAS bf16_t*)(lds + ((d + 1) * VTP + tok) * 2) = f2bf(bfhi(w[i]) * rkv); } } }
	v_pk_mul_f32 v[10:11], v[90:91], v[10:11]
	v_pk_mul_f32 v[14:15], v[14:15], v[162:163]
	v_cndmask_b32_e64 v11, v11, -v11, s[6:7]
	v_cndmask_b32_e64 v10, v10, -v10, s[6:7]
	v_pk_fma_f32 v[10:11], v[2:3], v[88:89], v[10:11]
	v_pk_mul_f32 v[2:3], v[4:5], v[6:7] op_sel_hi:[1,0]
	s_waitcnt lgkmcnt(0)
	v_pk_mul_f32 v[32:33], v[102:103], v[32:33]
	v_pk_mul_f32 v[2:3], v[2:3], v[8:9] op_sel:[0,1] op_sel_hi:[1,0]
	v_cndmask_b32_e64 v33, v33, -v33, s[6:7]
	v_cndmask_b32_e64 v32, v32, -v32, s[6:7]
	s_nop 1
	v_mov_b32_dpp v4, v2 quad_perm:[2,3,0,1] row_mask:0xf bank_mask:0xf
	v_mov_b32_dpp v5, v3 quad_perm:[2,3,0,1] row_mask:0xf bank_mask:0xf
	v_pk_fma_f32 v[12:13], v[12:13], v[100:101], v[32:33]
	s_nop 1
	v_mov_b32_dpp v32, v14 quad_perm:[2,3,0,1] row_mask:0xf bank_mask:0xf
	v_mov_b32_dpp v33, v15 quad_perm:[2,3,0,1] row_mask:0xf bank_mask:0xf
	v_pk_mul_f32 v[30:31], v[30:31], v[6:7] op_sel_hi:[1,0]
	s_waitcnt lgkmcnt(2)
	v_pk_mul_f32 v[4:5], v[82:83], v[4:5]
	v_pk_mul_f32 v[26:27], v[26:27], v[6:7] op_sel_hi:[1,0]
	v_cndmask_b32_e64 v5, v5, -v5, s[6:7]
	s_waitcnt lgkmcnt(0)
	v_pk_mul_f32 v[32:33], v[96:97], v[32:33]
	v_cndmask_b32_e64 v4, v4, -v4, s[6:7]
	v_lshl_add_u64 v[8:9], v[84:85], 0, s[8:9]
	v_pk_mul_f32 v[28:29], v[158:159], v[28:29]
	v_pk_mul_f32 v[24:25], v[124:125], v[24:25]
	v_pk_mul_f32 v[30:31], v[128:129], v[30:31]
	v_pk_mul_f32 v[26:27], v[120:121], v[26:27]
	v_cndmask_b32_e64 v33, v33, -v33, s[6:7]
	v_cndmask_b32_e64 v32, v32, -v32, s[6:7]
	v_pk_fma_f32 v[6:7], v[2:3], v[80:81], v[4:5]
	v_cvt_pk_bf16_f32 v2, v20, v21
	v_cvt_pk_bf16_f32 v3, v22, v23
	v_cvt_pk_bf16_f32 v4, v16, v17
	v_cvt_pk_bf16_f32 v5, v18, v19
	v_lshl_add_u64 v[16:17], v[8:9], 0, v[0:1]
	v_pk_fma_f32 v[14:15], v[14:15], v[94:95], v[32:33]
	global_store_dwordx4 v[16:17], v[2:5], off
	v_lshl_add_u64 v[16:17], v[8:9], 0, v[68:69]
	s_nop 0
	v_cvt_pk_bf16_f32 v2, v28, v29
	v_cvt_pk_bf16_f32 v3, v30, v31
	v_cvt_pk_bf16_f32 v4, v24, v25
	v_cvt_pk_bf16_f32 v5, v26, v27
	global_store_dwordx4 v[16:17], v[2:5], off
	s_nop 1
	v_cvt_pk_bf16_f32 v2, v12, v13
	v_cvt_pk_bf16_f32 v3, v14, v15
	v_cvt_pk_bf16_f32 v4, v10, v11
	v_cvt_pk_bf16_f32 v5, v6, v7
	v_lshl_add_u64 v[6:7], v[8:9], 0, v[70:71]
	global_store_dwordx4 v[6:7], v[2:5], off
	v_lshl_add_u64 v[6:7], v[78:79], 0, v[72:73]
	s_nop 0
	v_add_u32_e32 v11, s20, v143
	v_add_u32_e32 v176, 0xa000, v11
	s_add_i32 s20, s20, 2
	s_cmp_eq_u32 s20, 8
	v_mov_b32_e32 v2, v222
	v_mov_b32_e32 v3, v223
	v_mov_b32_e32 v4, v224
	v_mov_b32_e32 v5, v225
	v_mov_b32_e32 v6, v226
	v_mov_b32_e32 v7, v227
	v_mov_b32_e32 v8, v228
	v_mov_b32_e32 v9, v229
	v_lshlrev_b32_e32 v10, 16, v6
	v_and_b32_e32 v6, 0xffff0000, v6
	v_mul_f32_e32 v6, v76, v6
	v_cvt_pk_bf16_f32 v6, v6, s0
	ds_write_b16 v11, v6 offset:5120
	v_lshlrev_b32_e32 v6, 16, v7
	v_mul_f32_e32 v6, v76, v6
	v_cvt_pk_bf16_f32 v6, v6, s0
	ds_write_b16 v11, v6 offset:10240
	v_and_b32_e32 v6, 0xffff0000, v7
	v_mul_f32_e32 v6, v76, v6
	v_cvt_pk_bf16_f32 v6, v6, s0
	ds_write_b16 v11, v6 offset:15360
	v_lshlrev_b32_e32 v6, 16, v8
	v_mul_f32_e32 v6, v76, v6
	v_cvt_pk_bf16_f32 v6, v6, s0
	ds_write_b16 v11, v6 offset:20480
	v_and_b32_e32 v6, 0xffff0000, v8
	v_mul_f32_e32 v6, v76, v6
	v_cvt_pk_bf16_f32 v6, v6, s0
	ds_write_b16 v11, v6 offset:25600
	v_lshlrev_b32_e32 v6, 16, v9
	v_mul_f32_e32 v6, v76, v6
	v_cvt_pk_bf16_f32 v6, v6, s0
	ds_write_b16 v11, v6 offset:30720
	v_and_b32_e32 v6, 0xffff0000, v9
	v_mul_f32_e32 v6, v76, v6
	v_cvt_pk_bf16_f32 v6, v6, s0
	ds_write_b16 v11, v6 offset:35840
	v_lshlrev_b32_e32 v6, 16, v2
	v_and_b32_e32 v2, 0xffff0000, v2
	v_mul_f32_e32 v2, v76, v2
	v_cvt_pk_bf16_f32 v2, v2, s0
	ds_write_b16 v176, v2 offset:5120
	v_lshlrev_b32_e32 v2, 16, v3
	v_mul_f32_e32 v2, v76, v2
	v_cvt_pk_bf16_f32 v2, v2, s0
	ds_write_b16 v176, v2 offset:10240
	v_and_b32_e32 v2, 0xffff0000, v3
	v_mul_f32_e32 v2, v76, v2
	v_cvt_pk_bf16_f32 v2, v2, s0
	ds_write_b16 v176, v2 offset:15360
	v_lshlrev_b32_e32 v2, 16, v4
	v_mul_f32_e32 v2, v76, v2
	v_cvt_pk_bf16_f32 v2, v2, s0
	ds_write_b16 v176, v2 offset:20480
	v_and_b32_e32 v2, 0xffff0000, v4
	v_mul_f32_e32 v2, v76, v2
	v_cvt_pk_bf16_f32 v2, v2, s0
	ds_write_b16 v176, v2 offset:25600
	v_lshlrev_b32_e32 v2, 16, v5
	v_mul_f32_e32 v2, v76, v2
	v_cvt_pk_bf16_f32 v2, v2, s0
	ds_write_b16 v176, v2 offset:30720
	v_and_b32_e32 v2, 0xffff0000, v5
	v_mul_f32_e32 v10, v76, v10
	v_mul_f32_e32 v6, v76, v6
	v_mul_f32_e32 v2, v76, v2
	v_cvt_pk_bf16_f32 v10, v10, s0
	v_cvt_pk_bf16_f32 v6, v6, s0
	v_cvt_pk_bf16_f32 v2, v2, s0
	ds_write_b16 v11, v10
	ds_write_b16 v176, v6
	ds_write_b16 v176, v2 offset:35840
	s_cbranch_scc1 .LBB0_784
